# GEMM_IN round rotation only when the grid is the expected 512 workgroups (otherwise the original tile order)
# baseline (speedup 1.0000x reference)
.LBB0_271:
	v_and_b32_e32 v150, 63, v128
	v_lshrrev_b32_e32 v151, 6, v128
	v_lshrrev_b32_e32 v152, 3, v150
	v_readfirstlane_b32 s0, v151
	v_and_b32_e32 v153, 7, v150
	v_xor_b32_e32 v153, v153, v152
	v_lshlrev_b32_e32 v153, 4, v153
	v_lshl_add_u32 v153, v152, 11, v153
	s_lshl_b32 s1, s0, 16
	v_add_u32_e32 v132, s1, v153
	v_add_u32_e32 v133, 0x3c00, v132
	v_add_u32_e32 v134, 0x7800, v132
	v_add_u32_e32 v135, 0xb400, v132
	s_lshl_b32 s1, s0, 12
	s_add_u32 s5, s1, 0
	s_add_u32 s6, s1, 16384
	s_add_u32 s7, s1, 45056
	s_add_u32 s8, s1, 61440
	v_and_b32_e32 v152, 15, v150
	v_lshrrev_b32_e32 v153, 4, v150
	v_and_b32_e32 v154, 7, v152
	v_xor_b32_e32 v154, v154, v153
	v_lshlrev_b32_e32 v154, 4, v154
	v_lshl_add_u32 v154, v152, 7, v154
	s_lshr_b32 s1, s0, 1
	s_lshl_b32 s1, s1, 13
	v_add_u32_e32 v136, s1, v154
	v_xor_b32_e32 v137, 64, v136
	v_add_u32_e32 v138, 0xb000, v136
	v_add_u32_e32 v139, 0xb000, v137
	s_and_b32 s1, s0, 1
	s_lshl_b32 s1, s1, 13
	s_add_u32 s1, s1, 16384
	v_add_u32_e32 v140, s1, v154
	v_xor_b32_e32 v141, 64, v140
	v_add_u32_e32 v142, 0xb000, v140
	v_add_u32_e32 v143, 0xb000, v141
	s_and_b32 s1, s0, 1
	s_lshl_b32 s1, s1, 6
	v_add_u32_e32 v152, s1, v152
	v_mov_b32_e32 v154, 0x4a00
	v_mul_lo_u32 v152, v152, v154
	v_and_b32_e32 v154, 1, v153
	v_lshrrev_b32_e32 v153, 1, v153
	v_lshlrev_b32_e32 v153, 4, v153
	v_lshl_or_b32 v153, v154, 5, v153
	s_lshr_b32 s1, s0, 1
	s_lshl_b32 s1, s1, 7
	v_add3_u32 v146, v152, v153, s1
	v_add_u32_e32 v147, 0x4a000, v146
	v_add_u32_e32 v148, 0x94000, v146
	v_add_u32_e32 v149, 0xde000, v146
	v_readlane_b32 s25, v252, 0
	s_mov_b32 s101, s25
	s_mov_b32 s100, -1
	v_readlane_b32 s0, v255, 35
	s_nop 0
	s_cmpk_eq_u32 s0, 0x200
	s_cbranch_scc0 .Lgin_noperm
	s_mov_b32 s100, 0
	s_and_b32 s0, s25, 7
	s_lshl_b32 s0, s0, 9
	s_add_i32 s25, s25, s0
.Lgin_noperm:
	v_readlane_b32 s98, v252, 0
	s_and_b32 s99, s98, 7
	s_lshr_b32 s98, s98, 3
	s_lshl_b32 s99, s99, 1
	s_add_i32 s98, s98, s99
	s_and_b32 s98, s98, 15
	s_and_b32 s0, s25, 63
	s_lshr_b32 s1, s25, 6
	s_mul_i32 s4, s70, 0x1280000
	s_lshl_b32 s39, s1, 18
	s_add_u32 s4, s4, s39
	s_add_u32 s26, s96, s4
	s_addc_u32 s27, s97, 0
	s_lshl_b32 s4, s0, 18
	s_add_u32 s4, s4, 0x82a6100
	s_add_u32 s28, s96, s4
	s_addc_u32 s29, s97, 0
	s_lshl_b32 s0, s98, 7
	s_add_u32 s26, s26, s0
	s_addc_u32 s27, s27, 0
	s_add_u32 s28, s28, s0
	s_addc_u32 s29, s29, 0
	s_mov_b32 s99, s98
	s_mov_b32 m0, s5
	s_nop 0
	global_load_lds_dwordx4 v132, s[26:27] offset:0
	global_load_lds_dwordx4 v133, s[26:27] offset:1024
	global_load_lds_dwordx4 v134, s[26:27] offset:2048
	global_load_lds_dwordx4 v135, s[26:27] offset:3072
	s_mov_b32 m0, s6
	s_nop 0
	global_load_lds_dwordx4 v132, s[28:29] offset:0
	global_load_lds_dwordx4 v133, s[28:29] offset:1024
	global_load_lds_dwordx4 v134, s[28:29] offset:2048
	global_load_lds_dwordx4 v135, s[28:29] offset:3072
	s_waitcnt vmcnt(0)
.Lgin_tile:
	s_waitcnt vmcnt(8)
	s_barrier
	s_add_i32 s99, s99, 1
	s_cmp_eq_u32 s99, 16
	s_movk_i32 s0, 0x80
	s_cselect_b32 s0, 0xfffff880, s0
	s_cselect_b32 s99, 0, s99
	s_ashr_i32 s1, s0, 31
	s_add_u32 s26, s26, s0
	s_addc_u32 s27, s27, s1
	s_add_u32 s28, s28, s0
	s_addc_u32 s29, s29, s1
	s_mov_b32 m0, s7
	s_nop 0
	global_load_lds_dwordx4 v132, s[26:27] offset:0
	global_load_lds_dwordx4 v133, s[26:27] offset:1024
	global_load_lds_dwordx4 v134, s[26:27] offset:2048
	global_load_lds_dwordx4 v135, s[26:27] offset:3072
	s_mov_b32 m0, s8
	s_nop 0
	global_load_lds_dwordx4 v132, s[28:29] offset:0
	global_load_lds_dwordx4 v133, s[28:29] offset:1024
	global_load_lds_dwordx4 v134, s[28:29] offset:2048
	global_load_lds_dwordx4 v135, s[28:29] offset:3072
	ds_read_b128 v[64:67], v136 offset:0
	ds_read_b128 v[96:99], v140 offset:0
	ds_read_b128 v[100:103], v140 offset:2048
	ds_read_b128 v[104:107], v140 offset:4096
	ds_read_b128 v[108:111], v140 offset:6144
	ds_read_b128 v[68:71], v136 offset:2048
	ds_read_b128 v[72:75], v136 offset:4096
	ds_read_b128 v[76:79], v136 offset:6144
	s_waitcnt lgkmcnt(3)
	v_mfma_f32_16x16x32_bf16 v[0:3], v[64:67], v[96:99], 0
	v_mfma_f32_16x16x32_bf16 v[4:7], v[64:67], v[100:103], 0
	ds_read_b128 v[80:83], v137 offset:0
	v_mfma_f32_16x16x32_bf16 v[8:11], v[64:67], v[104:107], 0
	v_mfma_f32_16x16x32_bf16 v[12:15], v[64:67], v[108:111], 0
	ds_read_b128 v[112:115], v141 offset:0
	s_waitcnt lgkmcnt(4)
	v_mfma_f32_16x16x32_bf16 v[16:19], v[68:71], v[96:99], 0
	v_mfma_f32_16x16x32_bf16 v[20:23], v[68:71], v[100:103], 0
	ds_read_b128 v[116:119], v141 offset:2048
	v_mfma_f32_16x16x32_bf16 v[24:27], v[68:71], v[104:107], 0
	v_mfma_f32_16x16x32_bf16 v[28:31], v[68:71], v[108:111], 0
	ds_read_b128 v[120:123], v141 offset:4096
	s_waitcnt lgkmcnt(5)
	v_mfma_f32_16x16x32_bf16 v[32:35], v[72:75], v[96:99], 0
	v_mfma_f32_16x16x32_bf16 v[36:39], v[72:75], v[100:103], 0
	ds_read_b128 v[124:127], v141 offset:6144
	v_mfma_f32_16x16x32_bf16 v[40:43], v[72:75], v[104:107], 0
	v_mfma_f32_16x16x32_bf16 v[44:47], v[72:75], v[108:111], 0
	ds_read_b128 v[84:87], v137 offset:2048
	s_waitcnt lgkmcnt(6)
	v_mfma_f32_16x16x32_bf16 v[48:51], v[76:79], v[96:99], 0
	v_mfma_f32_16x16x32_bf16 v[52:55], v[76:79], v[100:103], 0
	ds_read_b128 v[88:91], v137 offset:4096
	v_mfma_f32_16x16x32_bf16 v[56:59], v[76:79], v[104:107], 0
	v_mfma_f32_16x16x32_bf16 v[60:63], v[76:79], v[108:111], 0
	ds_read_b128 v[92:95], v137 offset:6144
	s_waitcnt lgkmcnt(3)
	v_mfma_f32_16x16x32_bf16 v[0:3], v[80:83], v[112:115], v[0:3]
	v_mfma_f32_16x16x32_bf16 v[4:7], v[80:83], v[116:119], v[4:7]
	v_mfma_f32_16x16x32_bf16 v[8:11], v[80:83], v[120:123], v[8:11]
	v_mfma_f32_16x16x32_bf16 v[12:15], v[80:83], v[124:127], v[12:15]
	s_waitcnt lgkmcnt(2)
	v_mfma_f32_16x16x32_bf16 v[16:19], v[84:87], v[112:115], v[16:19]
	v_mfma_f32_16x16x32_bf16 v[20:23], v[84:87], v[116:119], v[20:23]
	v_mfma_f32_16x16x32_bf16 v[24:27], v[84:87], v[120:123], v[24:27]
	v_mfma_f32_16x16x32_bf16 v[28:31], v[84:87], v[124:127], v[28:31]
	s_waitcnt lgkmcnt(1)
	v_mfma_f32_16x16x32_bf16 v[32:35], v[88:91], v[112:115], v[32:35]
	v_mfma_f32_16x16x32_bf16 v[36:39], v[88:91], v[116:119], v[36:39]
	v_mfma_f32_16x16x32_bf16 v[40:43], v[88:91], v[120:123], v[40:43]
	v_mfma_f32_16x16x32_bf16 v[44:47], v[88:91], v[124:127], v[44:47]
	s_waitcnt lgkmcnt(0)
	v_mfma_f32_16x16x32_bf16 v[48:51], v[92:95], v[112:115], v[48:51]
	v_mfma_f32_16x16x32_bf16 v[52:55], v[92:95], v[116:119], v[52:55]
	v_mfma_f32_16x16x32_bf16 v[56:59], v[92:95], v[120:123], v[56:59]
	v_mfma_f32_16x16x32_bf16 v[60:63], v[92:95], v[124:127], v[60:63]
	s_waitcnt vmcnt(0)
	s_barrier
	s_add_i32 s99, s99, 1
	s_cmp_eq_u32 s99, 16
	s_movk_i32 s0, 0x80
	s_cselect_b32 s0, 0xfffff880, s0
	s_cselect_b32 s99, 0, s99
	s_ashr_i32 s1, s0, 31
	s_add_u32 s26, s26, s0
	s_addc_u32 s27, s27, s1
	s_add_u32 s28, s28, s0
	s_addc_u32 s29, s29, s1
	s_mov_b32 m0, s5
	s_nop 0
	global_load_lds_dwordx4 v132, s[26:27] offset:0
	global_load_lds_dwordx4 v133, s[26:27] offset:1024
	global_load_lds_dwordx4 v134, s[26:27] offset:2048
	global_load_lds_dwordx4 v135, s[26:27] offset:3072
	s_mov_b32 m0, s6
	s_nop 0
	global_load_lds_dwordx4 v132, s[28:29] offset:0
	global_load_lds_dwordx4 v133, s[28:29] offset:1024
	global_load_lds_dwordx4 v134, s[28:29] offset:2048
	global_load_lds_dwordx4 v135, s[28:29] offset:3072
	ds_read_b128 v[64:67], v138 offset:0
	ds_read_b128 v[96:99], v142 offset:0
	ds_read_b128 v[100:103], v142 offset:2048
	ds_read_b128 v[104:107], v142 offset:4096
	ds_read_b128 v[108:111], v142 offset:6144
	ds_read_b128 v[68:71], v138 offset:2048
	ds_read_b128 v[72:75], v138 offset:4096
	ds_read_b128 v[76:79], v138 offset:6144
	s_waitcnt lgkmcnt(3)
	v_mfma_f32_16x16x32_bf16 v[0:3], v[64:67], v[96:99], v[0:3]
	v_mfma_f32_16x16x32_bf16 v[4:7], v[64:67], v[100:103], v[4:7]
	ds_read_b128 v[80:83], v139 offset:0
	v_mfma_f32_16x16x32_bf16 v[8:11], v[64:67], v[104:107], v[8:11]
	v_mfma_f32_16x16x32_bf16 v[12:15], v[64:67], v[108:111], v[12:15]
	ds_read_b128 v[112:115], v143 offset:0
	s_waitcnt lgkmcnt(4)
	v_mfma_f32_16x16x32_bf16 v[16:19], v[68:71], v[96:99], v[16:19]
	v_mfma_f32_16x16x32_bf16 v[20:23], v[68:71], v[100:103], v[20:23]
	ds_read_b128 v[116:119], v143 offset:2048
	v_mfma_f32_16x16x32_bf16 v[24:27], v[68:71], v[104:107], v[24:27]
	v_mfma_f32_16x16x32_bf16 v[28:31], v[68:71], v[108:111], v[28:31]
	ds_read_b128 v[120:123], v143 offset:4096
	s_waitcnt lgkmcnt(5)
	v_mfma_f32_16x16x32_bf16 v[32:35], v[72:75], v[96:99], v[32:35]
	v_mfma_f32_16x16x32_bf16 v[36:39], v[72:75], v[100:103], v[36:39]
	ds_read_b128 v[124:127], v143 offset:6144
	v_mfma_f32_16x16x32_bf16 v[40:43], v[72:75], v[104:107], v[40:43]
	v_mfma_f32_16x16x32_bf16 v[44:47], v[72:75], v[108:111], v[44:47]
	ds_read_b128 v[84:87], v139 offset:2048
	s_waitcnt lgkmcnt(6)
	v_mfma_f32_16x16x32_bf16 v[48:51], v[76:79], v[96:99], v[48:51]
	v_mfma_f32_16x16x32_bf16 v[52:55], v[76:79], v[100:103], v[52:55]
	ds_read_b128 v[88:91], v139 offset:4096
	v_mfma_f32_16x16x32_bf16 v[56:59], v[76:79], v[104:107], v[56:59]
	v_mfma_f32_16x16x32_bf16 v[60:63], v[76:79], v[108:111], v[60:63]
	ds_read_b128 v[92:95], v139 offset:6144
	s_waitcnt lgkmcnt(3)
	v_mfma_f32_16x16x32_bf16 v[0:3], v[80:83], v[112:115], v[0:3]
	v_mfma_f32_16x16x32_bf16 v[4:7], v[80:83], v[116:119], v[4:7]
	v_mfma_f32_16x16x32_bf16 v[8:11], v[80:83], v[120:123], v[8:11]
	v_mfma_f32_16x16x32_bf16 v[12:15], v[80:83], v[124:127], v[12:15]
	s_waitcnt lgkmcnt(2)
	v_mfma_f32_16x16x32_bf16 v[16:19], v[84:87], v[112:115], v[16:19]
	v_mfma_f32_16x16x32_bf16 v[20:23], v[84:87], v[116:119], v[20:23]
	v_mfma_f32_16x16x32_bf16 v[24:27], v[84:87], v[120:123], v[24:27]
	v_mfma_f32_16x16x32_bf16 v[28:31], v[84:87], v[124:127], v[28:31]
	s_waitcnt lgkmcnt(1)
	v_mfma_f32_16x16x32_bf16 v[32:35], v[88:91], v[112:115], v[32:35]
	v_mfma_f32_16x16x32_bf16 v[36:39], v[88:91], v[116:119], v[36:39]
	v_mfma_f32_16x16x32_bf16 v[40:43], v[88:91], v[120:123], v[40:43]
	v_mfma_f32_16x16x32_bf16 v[44:47], v[88:91], v[124:127], v[44:47]
	s_waitcnt lgkmcnt(0)
	v_mfma_f32_16x16x32_bf16 v[48:51], v[92:95], v[112:115], v[48:51]
	v_mfma_f32_16x16x32_bf16 v[52:55], v[92:95], v[116:119], v[52:55]
	v_mfma_f32_16x16x32_bf16 v[56:59], v[92:95], v[120:123], v[56:59]
	v_mfma_f32_16x16x32_bf16 v[60:63], v[92:95], v[124:127], v[60:63]
	s_waitcnt vmcnt(0)
	s_barrier
	s_add_i32 s99, s99, 1
	s_cmp_eq_u32 s99, 16
	s_movk_i32 s0, 0x80
	s_cselect_b32 s0, 0xfffff880, s0
	s_cselect_b32 s99, 0, s99
	s_ashr_i32 s1, s0, 31
	s_add_u32 s26, s26, s0
	s_addc_u32 s27, s27, s1
	s_add_u32 s28, s28, s0
	s_addc_u32 s29, s29, s1
	s_mov_b32 m0, s7
	s_nop 0
	global_load_lds_dwordx4 v132, s[26:27] offset:0
	global_load_lds_dwordx4 v133, s[26:27] offset:1024
	global_load_lds_dwordx4 v134, s[26:27] offset:2048
	global_load_lds_dwordx4 v135, s[26:27] offset:3072
	s_mov_b32 m0, s8
	s_nop 0
	global_load_lds_dwordx4 v132, s[28:29] offset:0
	global_load_lds_dwordx4 v133, s[28:29] offset:1024
	global_load_lds_dwordx4 v134, s[28:29] offset:2048
	global_load_lds_dwordx4 v135, s[28:29] offset:3072
	ds_read_b128 v[64:67], v136 offset:0
	ds_read_b128 v[96:99], v140 offset:0
	ds_read_b128 v[100:103], v140 offset:2048
	ds_read_b128 v[104:107], v140 offset:4096
	ds_read_b128 v[108:111], v140 offset:6144
	ds_read_b128 v[68:71], v136 offset:2048
	ds_read_b128 v[72:75], v136 offset:4096
	ds_read_b128 v[76:79], v136 offset:6144
	s_waitcnt lgkmcnt(3)
	v_mfma_f32_16x16x32_bf16 v[0:3], v[64:67], v[96:99], v[0:3]
	v_mfma_f32_16x16x32_bf16 v[4:7], v[64:67], v[100:103], v[4:7]
	ds_read_b128 v[80:83], v137 offset:0
	v_mfma_f32_16x16x32_bf16 v[8:11], v[64:67], v[104:107], v[8:11]
	v_mfma_f32_16x16x32_bf16 v[12:15], v[64:67], v[108:111], v[12:15]
	ds_read_b128 v[112:115], v141 offset:0
	s_waitcnt lgkmcnt(4)
	v_mfma_f32_16x16x32_bf16 v[16:19], v[68:71], v[96:99], v[16:19]
	v_mfma_f32_16x16x32_bf16 v[20:23], v[68:71], v[100:103], v[20:23]
	ds_read_b128 v[116:119], v141 offset:2048
	v_mfma_f32_16x16x32_bf16 v[24:27], v[68:71], v[104:107], v[24:27]
	v_mfma_f32_16x16x32_bf16 v[28:31], v[68:71], v[108:111], v[28:31]
	ds_read_b128 v[120:123], v141 offset:4096
	s_waitcnt lgkmcnt(5)
	v_mfma_f32_16x16x32_bf16 v[32:35], v[72:75], v[96:99], v[32:35]
	v_mfma_f32_16x16x32_bf16 v[36:39], v[72:75], v[100:103], v[36:39]
	ds_read_b128 v[124:127], v141 offset:6144
	v_mfma_f32_16x16x32_bf16 v[40:43], v[72:75], v[104:107], v[40:43]
	v_mfma_f32_16x16x32_bf16 v[44:47], v[72:75], v[108:111], v[44:47]
	ds_read_b128 v[84:87], v137 offset:2048
	s_waitcnt lgkmcnt(6)
	v_mfma_f32_16x16x32_bf16 v[48:51], v[76:79], v[96:99], v[48:51]
	v_mfma_f32_16x16x32_bf16 v[52:55], v[76:79], v[100:103], v[52:55]
	ds_read_b128 v[88:91], v137 offset:4096
	v_mfma_f32_16x16x32_bf16 v[56:59], v[76:79], v[104:107], v[56:59]
	v_mfma_f32_16x16x32_bf16 v[60:63], v[76:79], v[108:111], v[60:63]
	ds_read_b128 v[92:95], v137 offset:6144
	s_waitcnt lgkmcnt(3)
	v_mfma_f32_16x16x32_bf16 v[0:3], v[80:83], v[112:115], v[0:3]
	v_mfma_f32_16x16x32_bf16 v[4:7], v[80:83], v[116:119], v[4:7]
	v_mfma_f32_16x16x32_bf16 v[8:11], v[80:83], v[120:123], v[8:11]
	v_mfma_f32_16x16x32_bf16 v[12:15], v[80:83], v[124:127], v[12:15]
	s_waitcnt lgkmcnt(2)
	v_mfma_f32_16x16x32_bf16 v[16:19], v[84:87], v[112:115], v[16:19]
	v_mfma_f32_16x16x32_bf16 v[20:23], v[84:87], v[116:119], v[20:23]
	v_mfma_f32_16x16x32_bf16 v[24:27], v[84:87], v[120:123], v[24:27]
	v_mfma_f32_16x16x32_bf16 v[28:31], v[84:87], v[124:127], v[28:31]
	s_waitcnt lgkmcnt(1)
	v_mfma_f32_16x16x32_bf16 v[32:35], v[88:91], v[112:115], v[32:35]
	v_mfma_f32_16x16x32_bf16 v[36:39], v[88:91], v[116:119], v[36:39]
	v_mfma_f32_16x16x32_bf16 v[40:43], v[88:91], v[120:123], v[40:43]
	v_mfma_f32_16x16x32_bf16 v[44:47], v[88:91], v[124:127], v[44:47]
	s_waitcnt lgkmcnt(0)
	v_mfma_f32_16x16x32_bf16 v[48:51], v[92:95], v[112:115], v[48:51]
	v_mfma_f32_16x16x32_bf16 v[52:55], v[92:95], v[116:119], v[52:55]
	v_mfma_f32_16x16x32_bf16 v[56:59], v[92:95], v[120:123], v[56:59]
	v_mfma_f32_16x16x32_bf16 v[60:63], v[92:95], v[124:127], v[60:63]
	s_waitcnt vmcnt(0)
	s_barrier
	s_add_i32 s99, s99, 1
	s_cmp_eq_u32 s99, 16
	s_movk_i32 s0, 0x80
	s_cselect_b32 s0, 0xfffff880, s0
	s_cselect_b32 s99, 0, s99
	s_ashr_i32 s1, s0, 31
	s_add_u32 s26, s26, s0
	s_addc_u32 s27, s27, s1
	s_add_u32 s28, s28, s0
	s_addc_u32 s29, s29, s1
	s_mov_b32 m0, s5
	s_nop 0
	global_load_lds_dwordx4 v132, s[26:27] offset:0
	global_load_lds_dwordx4 v133, s[26:27] offset:1024
	global_load_lds_dwordx4 v134, s[26:27] offset:2048
	global_load_lds_dwordx4 v135, s[26:27] offset:3072
	s_mov_b32 m0, s6
	s_nop 0
	global_load_lds_dwordx4 v132, s[28:29] offset:0
	global_load_lds_dwordx4 v133, s[28:29] offset:1024
	global_load_lds_dwordx4 v134, s[28:29] offset:2048
	global_load_lds_dwordx4 v135, s[28:29] offset:3072
	ds_read_b128 v[64:67], v138 offset:0
	ds_read_b128 v[96:99], v142 offset:0
	ds_read_b128 v[100:103], v142 offset:2048
	ds_read_b128 v[104:107], v142 offset:4096
	ds_read_b128 v[108:111], v142 offset:6144
	ds_read_b128 v[68:71], v138 offset:2048
	ds_read_b128 v[72:75], v138 offset:4096
	ds_read_b128 v[76:79], v138 offset:6144
	s_waitcnt lgkmcnt(3)
	v_mfma_f32_16x16x32_bf16 v[0:3], v[64:67], v[96:99], v[0:3]
	v_mfma_f32_16x16x32_bf16 v[4:7], v[64:67], v[100:103], v[4:7]
	ds_read_b128 v[80:83], v139 offset:0
	v_mfma_f32_16x16x32_bf16 v[8:11], v[64:67], v[104:107], v[8:11]
	v_mfma_f32_16x16x32_bf16 v[12:15], v[64:67], v[108:111], v[12:15]
	ds_read_b128 v[112:115], v143 offset:0
	s_waitcnt lgkmcnt(4)
	v_mfma_f32_16x16x32_bf16 v[16:19], v[68:71], v[96:99], v[16:19]
	v_mfma_f32_16x16x32_bf16 v[20:23], v[68:71], v[100:103], v[20:23]
	ds_read_b128 v[116:119], v143 offset:2048
	v_mfma_f32_16x16x32_bf16 v[24:27], v[68:71], v[104:107], v[24:27]
	v_mfma_f32_16x16x32_bf16 v[28:31], v[68:71], v[108:111], v[28:31]
	ds_read_b128 v[120:123], v143 offset:4096
	s_waitcnt lgkmcnt(5)
	v_mfma_f32_16x16x32_bf16 v[32:35], v[72:75], v[96:99], v[32:35]
	v_mfma_f32_16x16x32_bf16 v[36:39], v[72:75], v[100:103], v[36:39]
	ds_read_b128 v[124:127], v143 offset:6144
	v_mfma_f32_16x16x32_bf16 v[40:43], v[72:75], v[104:107], v[40:43]
	v_mfma_f32_16x16x32_bf16 v[44:47], v[72:75], v[108:111], v[44:47]
	ds_read_b128 v[84:87], v139 offset:2048
	s_waitcnt lgkmcnt(6)
	v_mfma_f32_16x16x32_bf16 v[48:51], v[76:79], v[96:99], v[48:51]
	v_mfma_f32_16x16x32_bf16 v[52:55], v[76:79], v[100:103], v[52:55]
	ds_read_b128 v[88:91], v139 offset:4096
	v_mfma_f32_16x16x32_bf16 v[56:59], v[76:79], v[104:107], v[56:59]
	v_mfma_f32_16x16x32_bf16 v[60:63], v[76:79], v[108:111], v[60:63]
	ds_read_b128 v[92:95], v139 offset:6144
	s_waitcnt lgkmcnt(3)
	v_mfma_f32_16x16x32_bf16 v[0:3], v[80:83], v[112:115], v[0:3]
	v_mfma_f32_16x16x32_bf16 v[4:7], v[80:83], v[116:119], v[4:7]
	v_mfma_f32_16x16x32_bf16 v[8:11], v[80:83], v[120:123], v[8:11]
	v_mfma_f32_16x16x32_bf16 v[12:15], v[80:83], v[124:127], v[12:15]
	s_waitcnt lgkmcnt(2)
	v_mfma_f32_16x16x32_bf16 v[16:19], v[84:87], v[112:115], v[16:19]
	v_mfma_f32_16x16x32_bf16 v[20:23], v[84:87], v[116:119], v[20:23]
	v_mfma_f32_16x16x32_bf16 v[24:27], v[84:87], v[120:123], v[24:27]
	v_mfma_f32_16x16x32_bf16 v[28:31], v[84:87], v[124:127], v[28:31]
	s_waitcnt lgkmcnt(1)
	v_mfma_f32_16x16x32_bf16 v[32:35], v[88:91], v[112:115], v[32:35]
	v_mfma_f32_16x16x32_bf16 v[36:39], v[88:91], v[116:119], v[36:39]
	v_mfma_f32_16x16x32_bf16 v[40:43], v[88:91], v[120:123], v[40:43]
	v_mfma_f32_16x16x32_bf16 v[44:47], v[88:91], v[124:127], v[44:47]
	s_waitcnt lgkmcnt(0)
	v_mfma_f32_16x16x32_bf16 v[48:51], v[92:95], v[112:115], v[48:51]
	v_mfma_f32_16x16x32_bf16 v[52:55], v[92:95], v[116:119], v[52:55]
	v_mfma_f32_16x16x32_bf16 v[56:59], v[92:95], v[120:123], v[56:59]
	v_mfma_f32_16x16x32_bf16 v[60:63], v[92:95], v[124:127], v[60:63]
	s_waitcnt vmcnt(0)
	s_barrier
	s_add_i32 s99, s99, 1
	s_cmp_eq_u32 s99, 16
	s_movk_i32 s0, 0x80
	s_cselect_b32 s0, 0xfffff880, s0
	s_cselect_b32 s99, 0, s99
	s_ashr_i32 s1, s0, 31
	s_add_u32 s26, s26, s0
	s_addc_u32 s27, s27, s1
	s_add_u32 s28, s28, s0
	s_addc_u32 s29, s29, s1
	s_mov_b32 m0, s7
	s_nop 0
	global_load_lds_dwordx4 v132, s[26:27] offset:0
	global_load_lds_dwordx4 v133, s[26:27] offset:1024
	global_load_lds_dwordx4 v134, s[26:27] offset:2048
	global_load_lds_dwordx4 v135, s[26:27] offset:3072
	s_mov_b32 m0, s8
	s_nop 0
	global_load_lds_dwordx4 v132, s[28:29] offset:0
	global_load_lds_dwordx4 v133, s[28:29] offset:1024
	global_load_lds_dwordx4 v134, s[28:29] offset:2048
	global_load_lds_dwordx4 v135, s[28:29] offset:3072
	ds_read_b128 v[64:67], v136 offset:0
	ds_read_b128 v[96:99], v140 offset:0
	ds_read_b128 v[100:103], v140 offset:2048
	ds_read_b128 v[104:107], v140 offset:4096
	ds_read_b128 v[108:111], v140 offset:6144
	ds_read_b128 v[68:71], v136 offset:2048
	ds_read_b128 v[72:75], v136 offset:4096
	ds_read_b128 v[76:79], v136 offset:6144
	s_waitcnt lgkmcnt(3)
	v_mfma_f32_16x16x32_bf16 v[0:3], v[64:67], v[96:99], v[0:3]
	v_mfma_f32_16x16x32_bf16 v[4:7], v[64:67], v[100:103], v[4:7]
	ds_read_b128 v[80:83], v137 offset:0
	v_mfma_f32_16x16x32_bf16 v[8:11], v[64:67], v[104:107], v[8:11]
	v_mfma_f32_16x16x32_bf16 v[12:15], v[64:67], v[108:111], v[12:15]
	ds_read_b128 v[112:115], v141 offset:0
	s_waitcnt lgkmcnt(4)
	v_mfma_f32_16x16x32_bf16 v[16:19], v[68:71], v[96:99], v[16:19]
	v_mfma_f32_16x16x32_bf16 v[20:23], v[68:71], v[100:103], v[20:23]
	ds_read_b128 v[116:119], v141 offset:2048
	v_mfma_f32_16x16x32_bf16 v[24:27], v[68:71], v[104:107], v[24:27]
	v_mfma_f32_16x16x32_bf16 v[28:31], v[68:71], v[108:111], v[28:31]
	ds_read_b128 v[120:123], v141 offset:4096
	s_waitcnt lgkmcnt(5)
	v_mfma_f32_16x16x32_bf16 v[32:35], v[72:75], v[96:99], v[32:35]
	v_mfma_f32_16x16x32_bf16 v[36:39], v[72:75], v[100:103], v[36:39]
	ds_read_b128 v[124:127], v141 offset:6144
	v_mfma_f32_16x16x32_bf16 v[40:43], v[72:75], v[104:107], v[40:43]
	v_mfma_f32_16x16x32_bf16 v[44:47], v[72:75], v[108:111], v[44:47]
	ds_read_b128 v[84:87], v137 offset:2048
	s_waitcnt lgkmcnt(6)
	v_mfma_f32_16x16x32_bf16 v[48:51], v[76:79], v[96:99], v[48:51]
	v_mfma_f32_16x16x32_bf16 v[52:55], v[76:79], v[100:103], v[52:55]
	ds_read_b128 v[88:91], v137 offset:4096
	v_mfma_f32_16x16x32_bf16 v[56:59], v[76:79], v[104:107], v[56:59]
	v_mfma_f32_16x16x32_bf16 v[60:63], v[76:79], v[108:111], v[60:63]
	ds_read_b128 v[92:95], v137 offset:6144
	s_waitcnt lgkmcnt(3)
	v_mfma_f32_16x16x32_bf16 v[0:3], v[80:83], v[112:115], v[0:3]
	v_mfma_f32_16x16x32_bf16 v[4:7], v[80:83], v[116:119], v[4:7]
	v_mfma_f32_16x16x32_bf16 v[8:11], v[80:83], v[120:123], v[8:11]
	v_mfma_f32_16x16x32_bf16 v[12:15], v[80:83], v[124:127], v[12:15]
	s_waitcnt lgkmcnt(2)
	v_mfma_f32_16x16x32_bf16 v[16:19], v[84:87], v[112:115], v[16:19]
	v_mfma_f32_16x16x32_bf16 v[20:23], v[84:87], v[116:119], v[20:23]
	v_mfma_f32_16x16x32_bf16 v[24:27], v[84:87], v[120:123], v[24:27]
	v_mfma_f32_16x16x32_bf16 v[28:31], v[84:87], v[124:127], v[28:31]
	s_waitcnt lgkmcnt(1)
	v_mfma_f32_16x16x32_bf16 v[32:35], v[88:91], v[112:115], v[32:35]
	v_mfma_f32_16x16x32_bf16 v[36:39], v[88:91], v[116:119], v[36:39]
	v_mfma_f32_16x16x32_bf16 v[40:43], v[88:91], v[120:123], v[40:43]
	v_mfma_f32_16x16x32_bf16 v[44:47], v[88:91], v[124:127], v[44:47]
	s_waitcnt lgkmcnt(0)
	v_mfma_f32_16x16x32_bf16 v[48:51], v[92:95], v[112:115], v[48:51]
	v_mfma_f32_16x16x32_bf16 v[52:55], v[92:95], v[116:119], v[52:55]
	v_mfma_f32_16x16x32_bf16 v[56:59], v[92:95], v[120:123], v[56:59]
	v_mfma_f32_16x16x32_bf16 v[60:63], v[92:95], v[124:127], v[60:63]
	s_waitcnt vmcnt(0)
	s_barrier
	s_add_i32 s99, s99, 1
	s_cmp_eq_u32 s99, 16
	s_movk_i32 s0, 0x80
	s_cselect_b32 s0, 0xfffff880, s0
	s_cselect_b32 s99, 0, s99
	s_ashr_i32 s1, s0, 31
	s_add_u32 s26, s26, s0
	s_addc_u32 s27, s27, s1
	s_add_u32 s28, s28, s0
	s_addc_u32 s29, s29, s1
	s_mov_b32 m0, s5
	s_nop 0
	global_load_lds_dwordx4 v132, s[26:27] offset:0
	global_load_lds_dwordx4 v133, s[26:27] offset:1024
	global_load_lds_dwordx4 v134, s[26:27] offset:2048
	global_load_lds_dwordx4 v135, s[26:27] offset:3072
	s_mov_b32 m0, s6
	s_nop 0
	global_load_lds_dwordx4 v132, s[28:29] offset:0
	global_load_lds_dwordx4 v133, s[28:29] offset:1024
	global_load_lds_dwordx4 v134, s[28:29] offset:2048
	global_load_lds_dwordx4 v135, s[28:29] offset:3072
	ds_read_b128 v[64:67], v138 offset:0
	ds_read_b128 v[96:99], v142 offset:0
	ds_read_b128 v[100:103], v142 offset:2048
	ds_read_b128 v[104:107], v142 offset:4096
	ds_read_b128 v[108:111], v142 offset:6144
	ds_read_b128 v[68:71], v138 offset:2048
	ds_read_b128 v[72:75], v138 offset:4096
	ds_read_b128 v[76:79], v138 offset:6144
	s_waitcnt lgkmcnt(3)
	v_mfma_f32_16x16x32_bf16 v[0:3], v[64:67], v[96:99], v[0:3]
	v_mfma_f32_16x16x32_bf16 v[4:7], v[64:67], v[100:103], v[4:7]
	ds_read_b128 v[80:83], v139 offset:0
	v_mfma_f32_16x16x32_bf16 v[8:11], v[64:67], v[104:107], v[8:11]
	v_mfma_f32_16x16x32_bf16 v[12:15], v[64:67], v[108:111], v[12:15]
	ds_read_b128 v[112:115], v143 offset:0
	s_waitcnt lgkmcnt(4)
	v_mfma_f32_16x16x32_bf16 v[16:19], v[68:71], v[96:99], v[16:19]
	v_mfma_f32_16x16x32_bf16 v[20:23], v[68:71], v[100:103], v[20:23]
	ds_read_b128 v[116:119], v143 offset:2048
	v_mfma_f32_16x16x32_bf16 v[24:27], v[68:71], v[104:107], v[24:27]
	v_mfma_f32_16x16x32_bf16 v[28:31], v[68:71], v[108:111], v[28:31]
	ds_read_b128 v[120:123], v143 offset:4096
	s_waitcnt lgkmcnt(5)
	v_mfma_f32_16x16x32_bf16 v[32:35], v[72:75], v[96:99], v[32:35]
	v_mfma_f32_16x16x32_bf16 v[36:39], v[72:75], v[100:103], v[36:39]
	ds_read_b128 v[124:127], v143 offset:6144
	v_mfma_f32_16x16x32_bf16 v[40:43], v[72:75], v[104:107], v[40:43]
	v_mfma_f32_16x16x32_bf16 v[44:47], v[72:75], v[108:111], v[44:47]
	ds_read_b128 v[84:87], v139 offset:2048
	s_waitcnt lgkmcnt(6)
	v_mfma_f32_16x16x32_bf16 v[48:51], v[76:79], v[96:99], v[48:51]
	v_mfma_f32_16x16x32_bf16 v[52:55], v[76:79], v[100:103], v[52:55]
	ds_read_b128 v[88:91], v139 offset:4096
	v_mfma_f32_16x16x32_bf16 v[56:59], v[76:79], v[104:107], v[56:59]
	v_mfma_f32_16x16x32_bf16 v[60:63], v[76:79], v[108:111], v[60:63]
	ds_read_b128 v[92:95], v139 offset:6144
	s_waitcnt lgkmcnt(3)
	v_mfma_f32_16x16x32_bf16 v[0:3], v[80:83], v[112:115], v[0:3]
	v_mfma_f32_16x16x32_bf16 v[4:7], v[80:83], v[116:119], v[4:7]
	v_mfma_f32_16x16x32_bf16 v[8:11], v[80:83], v[120:123], v[8:11]
	v_mfma_f32_16x16x32_bf16 v[12:15], v[80:83], v[124:127], v[12:15]
	s_waitcnt lgkmcnt(2)
	v_mfma_f32_16x16x32_bf16 v[16:19], v[84:87], v[112:115], v[16:19]
	v_mfma_f32_16x16x32_bf16 v[20:23], v[84:87], v[116:119], v[20:23]
	v_mfma_f32_16x16x32_bf16 v[24:27], v[84:87], v[120:123], v[24:27]
	v_mfma_f32_16x16x32_bf16 v[28:31], v[84:87], v[124:127], v[28:31]
	s_waitcnt lgkmcnt(1)
	v_mfma_f32_16x16x32_bf16 v[32:35], v[88:91], v[112:115], v[32:35]
	v_mfma_f32_16x16x32_bf16 v[36:39], v[88:91], v[116:119], v[36:39]
	v_mfma_f32_16x16x32_bf16 v[40:43], v[88:91], v[120:123], v[40:43]
	v_mfma_f32_16x16x32_bf16 v[44:47], v[88:91], v[124:127], v[44:47]
	s_waitcnt lgkmcnt(0)
	v_mfma_f32_16x16x32_bf16 v[48:51], v[92:95], v[112:115], v[48:51]
	v_mfma_f32_16x16x32_bf16 v[52:55], v[92:95], v[116:119], v[52:55]
	v_mfma_f32_16x16x32_bf16 v[56:59], v[92:95], v[120:123], v[56:59]
	v_mfma_f32_16x16x32_bf16 v[60:63], v[92:95], v[124:127], v[60:63]
	s_waitcnt vmcnt(0)
	s_barrier
	s_add_i32 s99, s99, 1
	s_cmp_eq_u32 s99, 16
	s_movk_i32 s0, 0x80
	s_cselect_b32 s0, 0xfffff880, s0
	s_cselect_b32 s99, 0, s99
	s_ashr_i32 s1, s0, 31
	s_add_u32 s26, s26, s0
	s_addc_u32 s27, s27, s1
	s_add_u32 s28, s28, s0
	s_addc_u32 s29, s29, s1
	s_mov_b32 m0, s7
	s_nop 0
	global_load_lds_dwordx4 v132, s[26:27] offset:0
	global_load_lds_dwordx4 v133, s[26:27] offset:1024
	global_load_lds_dwordx4 v134, s[26:27] offset:2048
	global_load_lds_dwordx4 v135, s[26:27] offset:3072
	s_mov_b32 m0, s8
	s_nop 0
	global_load_lds_dwordx4 v132, s[28:29] offset:0
	global_load_lds_dwordx4 v133, s[28:29] offset:1024
	global_load_lds_dwordx4 v134, s[28:29] offset:2048
	global_load_lds_dwordx4 v135, s[28:29] offset:3072
	ds_read_b128 v[64:67], v136 offset:0
	ds_read_b128 v[96:99], v140 offset:0
	ds_read_b128 v[100:103], v140 offset:2048
	ds_read_b128 v[104:107], v140 offset:4096
	ds_read_b128 v[108:111], v140 offset:6144
	ds_read_b128 v[68:71], v136 offset:2048
	ds_read_b128 v[72:75], v136 offset:4096
	ds_read_b128 v[76:79], v136 offset:6144
	s_waitcnt lgkmcnt(3)
	v_mfma_f32_16x16x32_bf16 v[0:3], v[64:67], v[96:99], v[0:3]
	v_mfma_f32_16x16x32_bf16 v[4:7], v[64:67], v[100:103], v[4:7]
	ds_read_b128 v[80:83], v137 offset:0
	v_mfma_f32_16x16x32_bf16 v[8:11], v[64:67], v[104:107], v[8:11]
	v_mfma_f32_16x16x32_bf16 v[12:15], v[64:67], v[108:111], v[12:15]
	ds_read_b128 v[112:115], v141 offset:0
	s_waitcnt lgkmcnt(4)
	v_mfma_f32_16x16x32_bf16 v[16:19], v[68:71], v[96:99], v[16:19]
	v_mfma_f32_16x16x32_bf16 v[20:23], v[68:71], v[100:103], v[20:23]
	ds_read_b128 v[116:119], v141 offset:2048
	v_mfma_f32_16x16x32_bf16 v[24:27], v[68:71], v[104:107], v[24:27]
	v_mfma_f32_16x16x32_bf16 v[28:31], v[68:71], v[108:111], v[28:31]
	ds_read_b128 v[120:123], v141 offset:4096
	s_waitcnt lgkmcnt(5)
	v_mfma_f32_16x16x32_bf16 v[32:35], v[72:75], v[96:99], v[32:35]
	v_mfma_f32_16x16x32_bf16 v[36:39], v[72:75], v[100:103], v[36:39]
	ds_read_b128 v[124:127], v141 offset:6144
	v_mfma_f32_16x16x32_bf16 v[40:43], v[72:75], v[104:107], v[40:43]
	v_mfma_f32_16x16x32_bf16 v[44:47], v[72:75], v[108:111], v[44:47]
	ds_read_b128 v[84:87], v137 offset:2048
	s_waitcnt lgkmcnt(6)
	v_mfma_f32_16x16x32_bf16 v[48:51], v[76:79], v[96:99], v[48:51]
	v_mfma_f32_16x16x32_bf16 v[52:55], v[76:79], v[100:103], v[52:55]
	ds_read_b128 v[88:91], v137 offset:4096
	v_mfma_f32_16x16x32_bf16 v[56:59], v[76:79], v[104:107], v[56:59]
	v_mfma_f32_16x16x32_bf16 v[60:63], v[76:79], v[108:111], v[60:63]
	ds_read_b128 v[92:95], v137 offset:6144
	s_waitcnt lgkmcnt(3)
	v_mfma_f32_16x16x32_bf16 v[0:3], v[80:83], v[112:115], v[0:3]
	v_mfma_f32_16x16x32_bf16 v[4:7], v[80:83], v[116:119], v[4:7]
	v_mfma_f32_16x16x32_bf16 v[8:11], v[80:83], v[120:123], v[8:11]
	v_mfma_f32_16x16x32_bf16 v[12:15], v[80:83], v[124:127], v[12:15]
	s_waitcnt lgkmcnt(2)
	v_mfma_f32_16x16x32_bf16 v[16:19], v[84:87], v[112:115], v[16:19]
	v_mfma_f32_16x16x32_bf16 v[20:23], v[84:87], v[116:119], v[20:23]
	v_mfma_f32_16x16x32_bf16 v[24:27], v[84:87], v[120:123], v[24:27]
	v_mfma_f32_16x16x32_bf16 v[28:31], v[84:87], v[124:127], v[28:31]
	s_waitcnt lgkmcnt(1)
	v_mfma_f32_16x16x32_bf16 v[32:35], v[88:91], v[112:115], v[32:35]
	v_mfma_f32_16x16x32_bf16 v[36:39], v[88:91], v[116:119], v[36:39]
	v_mfma_f32_16x16x32_bf16 v[40:43], v[88:91], v[120:123], v[40:43]
	v_mfma_f32_16x16x32_bf16 v[44:47], v[88:91], v[124:127], v[44:47]
	s_waitcnt lgkmcnt(0)
	v_mfma_f32_16x16x32_bf16 v[48:51], v[92:95], v[112:115], v[48:51]
	v_mfma_f32_16x16x32_bf16 v[52:55], v[92:95], v[116:119], v[52:55]
	v_mfma_f32_16x16x32_bf16 v[56:59], v[92:95], v[120:123], v[56:59]
	v_mfma_f32_16x16x32_bf16 v[60:63], v[92:95], v[124:127], v[60:63]
	s_waitcnt vmcnt(0)
	s_barrier
	s_add_i32 s99, s99, 1
	s_cmp_eq_u32 s99, 16
	s_movk_i32 s0, 0x80
	s_cselect_b32 s0, 0xfffff880, s0
	s_cselect_b32 s99, 0, s99
	s_ashr_i32 s1, s0, 31
	s_add_u32 s26, s26, s0
	s_addc_u32 s27, s27, s1
	s_add_u32 s28, s28, s0
	s_addc_u32 s29, s29, s1
	s_mov_b32 m0, s5
	s_nop 0
	global_load_lds_dwordx4 v132, s[26:27] offset:0
	global_load_lds_dwordx4 v133, s[26:27] offset:1024
	global_load_lds_dwordx4 v134, s[26:27] offset:2048
	global_load_lds_dwordx4 v135, s[26:27] offset:3072
	s_mov_b32 m0, s6
	s_nop 0
	global_load_lds_dwordx4 v132, s[28:29] offset:0
	global_load_lds_dwordx4 v133, s[28:29] offset:1024
	global_load_lds_dwordx4 v134, s[28:29] offset:2048
	global_load_lds_dwordx4 v135, s[28:29] offset:3072
	ds_read_b128 v[64:67], v138 offset:0
	ds_read_b128 v[96:99], v142 offset:0
	ds_read_b128 v[100:103], v142 offset:2048
	ds_read_b128 v[104:107], v142 offset:4096
	ds_read_b128 v[108:111], v142 offset:6144
	ds_read_b128 v[68:71], v138 offset:2048
	ds_read_b128 v[72:75], v138 offset:4096
	ds_read_b128 v[76:79], v138 offset:6144
	s_waitcnt lgkmcnt(3)
	v_mfma_f32_16x16x32_bf16 v[0:3], v[64:67], v[96:99], v[0:3]
	v_mfma_f32_16x16x32_bf16 v[4:7], v[64:67], v[100:103], v[4:7]
	ds_read_b128 v[80:83], v139 offset:0
	v_mfma_f32_16x16x32_bf16 v[8:11], v[64:67], v[104:107], v[8:11]
	v_mfma_f32_16x16x32_bf16 v[12:15], v[64:67], v[108:111], v[12:15]
	ds_read_b128 v[112:115], v143 offset:0
	s_waitcnt lgkmcnt(4)
	v_mfma_f32_16x16x32_bf16 v[16:19], v[68:71], v[96:99], v[16:19]
	v_mfma_f32_16x16x32_bf16 v[20:23], v[68:71], v[100:103], v[20:23]
	ds_read_b128 v[116:119], v143 offset:2048
	v_mfma_f32_16x16x32_bf16 v[24:27], v[68:71], v[104:107], v[24:27]
	v_mfma_f32_16x16x32_bf16 v[28:31], v[68:71], v[108:111], v[28:31]
	ds_read_b128 v[120:123], v143 offset:4096
	s_waitcnt lgkmcnt(5)
	v_mfma_f32_16x16x32_bf16 v[32:35], v[72:75], v[96:99], v[32:35]
	v_mfma_f32_16x16x32_bf16 v[36:39], v[72:75], v[100:103], v[36:39]
	ds_read_b128 v[124:127], v143 offset:6144
	v_mfma_f32_16x16x32_bf16 v[40:43], v[72:75], v[104:107], v[40:43]
	v_mfma_f32_16x16x32_bf16 v[44:47], v[72:75], v[108:111], v[44:47]
	ds_read_b128 v[84:87], v139 offset:2048
	s_waitcnt lgkmcnt(6)
	v_mfma_f32_16x16x32_bf16 v[48:51], v[76:79], v[96:99], v[48:51]
	v_mfma_f32_16x16x32_bf16 v[52:55], v[76:79], v[100:103], v[52:55]
	ds_read_b128 v[88:91], v139 offset:4096
	v_mfma_f32_16x16x32_bf16 v[56:59], v[76:79], v[104:107], v[56:59]
	v_mfma_f32_16x16x32_bf16 v[60:63], v[76:79], v[108:111], v[60:63]
	ds_read_b128 v[92:95], v139 offset:6144
	s_waitcnt lgkmcnt(3)
	v_mfma_f32_16x16x32_bf16 v[0:3], v[80:83], v[112:115], v[0:3]
	v_mfma_f32_16x16x32_bf16 v[4:7], v[80:83], v[116:119], v[4:7]
	v_mfma_f32_16x16x32_bf16 v[8:11], v[80:83], v[120:123], v[8:11]
	v_mfma_f32_16x16x32_bf16 v[12:15], v[80:83], v[124:127], v[12:15]
	s_waitcnt lgkmcnt(2)
	v_mfma_f32_16x16x32_bf16 v[16:19], v[84:87], v[112:115], v[16:19]
	v_mfma_f32_16x16x32_bf16 v[20:23], v[84:87], v[116:119], v[20:23]
	v_mfma_f32_16x16x32_bf16 v[24:27], v[84:87], v[120:123], v[24:27]
	v_mfma_f32_16x16x32_bf16 v[28:31], v[84:87], v[124:127], v[28:31]
	s_waitcnt lgkmcnt(1)
	v_mfma_f32_16x16x32_bf16 v[32:35], v[88:91], v[112:115], v[32:35]
	v_mfma_f32_16x16x32_bf16 v[36:39], v[88:91], v[116:119], v[36:39]
	v_mfma_f32_16x16x32_bf16 v[40:43], v[88:91], v[120:123], v[40:43]
	v_mfma_f32_16x16x32_bf16 v[44:47], v[88:91], v[124:127], v[44:47]
	s_waitcnt lgkmcnt(0)
	v_mfma_f32_16x16x32_bf16 v[48:51], v[92:95], v[112:115], v[48:51]
	v_mfma_f32_16x16x32_bf16 v[52:55], v[92:95], v[116:119], v[52:55]
	v_mfma_f32_16x16x32_bf16 v[56:59], v[92:95], v[120:123], v[56:59]
	v_mfma_f32_16x16x32_bf16 v[60:63], v[92:95], v[124:127], v[60:63]
	s_waitcnt vmcnt(0)
	s_barrier
	s_add_i32 s99, s99, 1
	s_cmp_eq_u32 s99, 16
	s_movk_i32 s0, 0x80
	s_cselect_b32 s0, 0xfffff880, s0
	s_cselect_b32 s99, 0, s99
	s_ashr_i32 s1, s0, 31
	s_add_u32 s26, s26, s0
	s_addc_u32 s27, s27, s1
	s_add_u32 s28, s28, s0
	s_addc_u32 s29, s29, s1
	s_mov_b32 m0, s7
	s_nop 0
	global_load_lds_dwordx4 v132, s[26:27] offset:0
	global_load_lds_dwordx4 v133, s[26:27] offset:1024
	global_load_lds_dwordx4 v134, s[26:27] offset:2048
	global_load_lds_dwordx4 v135, s[26:27] offset:3072
	s_mov_b32 m0, s8
	s_nop 0
	global_load_lds_dwordx4 v132, s[28:29] offset:0
	global_load_lds_dwordx4 v133, s[28:29] offset:1024
	global_load_lds_dwordx4 v134, s[28:29] offset:2048
	global_load_lds_dwordx4 v135, s[28:29] offset:3072
	ds_read_b128 v[64:67], v136 offset:0
	ds_read_b128 v[96:99], v140 offset:0
	ds_read_b128 v[100:103], v140 offset:2048
	ds_read_b128 v[104:107], v140 offset:4096
	ds_read_b128 v[108:111], v140 offset:6144
	ds_read_b128 v[68:71], v136 offset:2048
	ds_read_b128 v[72:75], v136 offset:4096
	ds_read_b128 v[76:79], v136 offset:6144
	s_waitcnt lgkmcnt(3)
	v_mfma_f32_16x16x32_bf16 v[0:3], v[64:67], v[96:99], v[0:3]
	v_mfma_f32_16x16x32_bf16 v[4:7], v[64:67], v[100:103], v[4:7]
	ds_read_b128 v[80:83], v137 offset:0
	v_mfma_f32_16x16x32_bf16 v[8:11], v[64:67], v[104:107], v[8:11]
	v_mfma_f32_16x16x32_bf16 v[12:15], v[64:67], v[108:111], v[12:15]
	ds_read_b128 v[112:115], v141 offset:0
	s_waitcnt lgkmcnt(4)
	v_mfma_f32_16x16x32_bf16 v[16:19], v[68:71], v[96:99], v[16:19]
	v_mfma_f32_16x16x32_bf16 v[20:23], v[68:71], v[100:103], v[20:23]
	ds_read_b128 v[116:119], v141 offset:2048
	v_mfma_f32_16x16x32_bf16 v[24:27], v[68:71], v[104:107], v[24:27]
	v_mfma_f32_16x16x32_bf16 v[28:31], v[68:71], v[108:111], v[28:31]
	ds_read_b128 v[120:123], v141 offset:4096
	s_waitcnt lgkmcnt(5)
	v_mfma_f32_16x16x32_bf16 v[32:35], v[72:75], v[96:99], v[32:35]
	v_mfma_f32_16x16x32_bf16 v[36:39], v[72:75], v[100:103], v[36:39]
	ds_read_b128 v[124:127], v141 offset:6144
	v_mfma_f32_16x16x32_bf16 v[40:43], v[72:75], v[104:107], v[40:43]
	v_mfma_f32_16x16x32_bf16 v[44:47], v[72:75], v[108:111], v[44:47]
	ds_read_b128 v[84:87], v137 offset:2048
	s_waitcnt lgkmcnt(6)
	v_mfma_f32_16x16x32_bf16 v[48:51], v[76:79], v[96:99], v[48:51]
	v_mfma_f32_16x16x32_bf16 v[52:55], v[76:79], v[100:103], v[52:55]
	ds_read_b128 v[88:91], v137 offset:4096
	v_mfma_f32_16x16x32_bf16 v[56:59], v[76:79], v[104:107], v[56:59]
	v_mfma_f32_16x16x32_bf16 v[60:63], v[76:79], v[108:111], v[60:63]
	ds_read_b128 v[92:95], v137 offset:6144
	s_waitcnt lgkmcnt(3)
	v_mfma_f32_16x16x32_bf16 v[0:3], v[80:83], v[112:115], v[0:3]
	v_mfma_f32_16x16x32_bf16 v[4:7], v[80:83], v[116:119], v[4:7]
	v_mfma_f32_16x16x32_bf16 v[8:11], v[80:83], v[120:123], v[8:11]
	v_mfma_f32_16x16x32_bf16 v[12:15], v[80:83], v[124:127], v[12:15]
	s_waitcnt lgkmcnt(2)
	v_mfma_f32_16x16x32_bf16 v[16:19], v[84:87], v[112:115], v[16:19]
	v_mfma_f32_16x16x32_bf16 v[20:23], v[84:87], v[116:119], v[20:23]
	v_mfma_f32_16x16x32_bf16 v[24:27], v[84:87], v[120:123], v[24:27]
	v_mfma_f32_16x16x32_bf16 v[28:31], v[84:87], v[124:127], v[28:31]
	s_waitcnt lgkmcnt(1)
	v_mfma_f32_16x16x32_bf16 v[32:35], v[88:91], v[112:115], v[32:35]
	v_mfma_f32_16x16x32_bf16 v[36:39], v[88:91], v[116:119], v[36:39]
	v_mfma_f32_16x16x32_bf16 v[40:43], v[88:91], v[120:123], v[40:43]
	v_mfma_f32_16x16x32_bf16 v[44:47], v[88:91], v[124:127], v[44:47]
	s_waitcnt lgkmcnt(0)
	v_mfma_f32_16x16x32_bf16 v[48:51], v[92:95], v[112:115], v[48:51]
	v_mfma_f32_16x16x32_bf16 v[52:55], v[92:95], v[116:119], v[52:55]
	v_mfma_f32_16x16x32_bf16 v[56:59], v[92:95], v[120:123], v[56:59]
	v_mfma_f32_16x16x32_bf16 v[60:63], v[92:95], v[124:127], v[60:63]
	s_waitcnt vmcnt(0)
	s_barrier
	s_add_i32 s99, s99, 1
	s_cmp_eq_u32 s99, 16
	s_movk_i32 s0, 0x80
	s_cselect_b32 s0, 0xfffff880, s0
	s_cselect_b32 s99, 0, s99
	s_ashr_i32 s1, s0, 31
	s_add_u32 s26, s26, s0
	s_addc_u32 s27, s27, s1
	s_add_u32 s28, s28, s0
	s_addc_u32 s29, s29, s1
	s_mov_b32 m0, s5
	s_nop 0
	global_load_lds_dwordx4 v132, s[26:27] offset:0
	global_load_lds_dwordx4 v133, s[26:27] offset:1024
	global_load_lds_dwordx4 v134, s[26:27] offset:2048
	global_load_lds_dwordx4 v135, s[26:27] offset:3072
	s_mov_b32 m0, s6
	s_nop 0
	global_load_lds_dwordx4 v132, s[28:29] offset:0
	global_load_lds_dwordx4 v133, s[28:29] offset:1024
	global_load_lds_dwordx4 v134, s[28:29] offset:2048
	global_load_lds_dwordx4 v135, s[28:29] offset:3072
	ds_read_b128 v[64:67], v138 offset:0
	ds_read_b128 v[96:99], v142 offset:0
	ds_read_b128 v[100:103], v142 offset:2048
	ds_read_b128 v[104:107], v142 offset:4096
	ds_read_b128 v[108:111], v142 offset:6144
	ds_read_b128 v[68:71], v138 offset:2048
	ds_read_b128 v[72:75], v138 offset:4096
	ds_read_b128 v[76:79], v138 offset:6144
	s_waitcnt lgkmcnt(3)
	v_mfma_f32_16x16x32_bf16 v[0:3], v[64:67], v[96:99], v[0:3]
	v_mfma_f32_16x16x32_bf16 v[4:7], v[64:67], v[100:103], v[4:7]
	ds_read_b128 v[80:83], v139 offset:0
	v_mfma_f32_16x16x32_bf16 v[8:11], v[64:67], v[104:107], v[8:11]
	v_mfma_f32_16x16x32_bf16 v[12:15], v[64:67], v[108:111], v[12:15]
	ds_read_b128 v[112:115], v143 offset:0
	s_waitcnt lgkmcnt(4)
	v_mfma_f32_16x16x32_bf16 v[16:19], v[68:71], v[96:99], v[16:19]
	v_mfma_f32_16x16x32_bf16 v[20:23], v[68:71], v[100:103], v[20:23]
	ds_read_b128 v[116:119], v143 offset:2048
	v_mfma_f32_16x16x32_bf16 v[24:27], v[68:71], v[104:107], v[24:27]
	v_mfma_f32_16x16x32_bf16 v[28:31], v[68:71], v[108:111], v[28:31]
	ds_read_b128 v[120:123], v143 offset:4096
	s_waitcnt lgkmcnt(5)
	v_mfma_f32_16x16x32_bf16 v[32:35], v[72:75], v[96:99], v[32:35]
	v_mfma_f32_16x16x32_bf16 v[36:39], v[72:75], v[100:103], v[36:39]
	ds_read_b128 v[124:127], v143 offset:6144
	v_mfma_f32_16x16x32_bf16 v[40:43], v[72:75], v[104:107], v[40:43]
	v_mfma_f32_16x16x32_bf16 v[44:47], v[72:75], v[108:111], v[44:47]
	ds_read_b128 v[84:87], v139 offset:2048
	s_waitcnt lgkmcnt(6)
	v_mfma_f32_16x16x32_bf16 v[48:51], v[76:79], v[96:99], v[48:51]
	v_mfma_f32_16x16x32_bf16 v[52:55], v[76:79], v[100:103], v[52:55]
	ds_read_b128 v[88:91], v139 offset:4096
	v_mfma_f32_16x16x32_bf16 v[56:59], v[76:79], v[104:107], v[56:59]
	v_mfma_f32_16x16x32_bf16 v[60:63], v[76:79], v[108:111], v[60:63]
	ds_read_b128 v[92:95], v139 offset:6144
	s_waitcnt lgkmcnt(3)
	v_mfma_f32_16x16x32_bf16 v[0:3], v[80:83], v[112:115], v[0:3]
	v_mfma_f32_16x16x32_bf16 v[4:7], v[80:83], v[116:119], v[4:7]
	v_mfma_f32_16x16x32_bf16 v[8:11], v[80:83], v[120:123], v[8:11]
	v_mfma_f32_16x16x32_bf16 v[12:15], v[80:83], v[124:127], v[12:15]
	s_waitcnt lgkmcnt(2)
	v_mfma_f32_16x16x32_bf16 v[16:19], v[84:87], v[112:115], v[16:19]
	v_mfma_f32_16x16x32_bf16 v[20:23], v[84:87], v[116:119], v[20:23]
	v_mfma_f32_16x16x32_bf16 v[24:27], v[84:87], v[120:123], v[24:27]
	v_mfma_f32_16x16x32_bf16 v[28:31], v[84:87], v[124:127], v[28:31]
	s_waitcnt lgkmcnt(1)
	v_mfma_f32_16x16x32_bf16 v[32:35], v[88:91], v[112:115], v[32:35]
	v_mfma_f32_16x16x32_bf16 v[36:39], v[88:91], v[116:119], v[36:39]
	v_mfma_f32_16x16x32_bf16 v[40:43], v[88:91], v[120:123], v[40:43]
	v_mfma_f32_16x16x32_bf16 v[44:47], v[88:91], v[124:127], v[44:47]
	s_waitcnt lgkmcnt(0)
	v_mfma_f32_16x16x32_bf16 v[48:51], v[92:95], v[112:115], v[48:51]
	v_mfma_f32_16x16x32_bf16 v[52:55], v[92:95], v[116:119], v[52:55]
	v_mfma_f32_16x16x32_bf16 v[56:59], v[92:95], v[120:123], v[56:59]
	v_mfma_f32_16x16x32_bf16 v[60:63], v[92:95], v[124:127], v[60:63]
	s_waitcnt vmcnt(0)
	s_barrier
	s_add_i32 s99, s99, 1
	s_cmp_eq_u32 s99, 16
	s_movk_i32 s0, 0x80
	s_cselect_b32 s0, 0xfffff880, s0
	s_cselect_b32 s99, 0, s99
	s_ashr_i32 s1, s0, 31
	s_add_u32 s26, s26, s0
	s_addc_u32 s27, s27, s1
	s_add_u32 s28, s28, s0
	s_addc_u32 s29, s29, s1
	s_mov_b32 m0, s7
	s_nop 0
	global_load_lds_dwordx4 v132, s[26:27] offset:0
	global_load_lds_dwordx4 v133, s[26:27] offset:1024
	global_load_lds_dwordx4 v134, s[26:27] offset:2048
	global_load_lds_dwordx4 v135, s[26:27] offset:3072
	s_mov_b32 m0, s8
	s_nop 0
	global_load_lds_dwordx4 v132, s[28:29] offset:0
	global_load_lds_dwordx4 v133, s[28:29] offset:1024
	global_load_lds_dwordx4 v134, s[28:29] offset:2048
	global_load_lds_dwordx4 v135, s[28:29] offset:3072
	ds_read_b128 v[64:67], v136 offset:0
	ds_read_b128 v[96:99], v140 offset:0
	ds_read_b128 v[100:103], v140 offset:2048
	ds_read_b128 v[104:107], v140 offset:4096
	ds_read_b128 v[108:111], v140 offset:6144
	ds_read_b128 v[68:71], v136 offset:2048
	ds_read_b128 v[72:75], v136 offset:4096
	ds_read_b128 v[76:79], v136 offset:6144
	s_waitcnt lgkmcnt(3)
	v_mfma_f32_16x16x32_bf16 v[0:3], v[64:67], v[96:99], v[0:3]
	v_mfma_f32_16x16x32_bf16 v[4:7], v[64:67], v[100:103], v[4:7]
	ds_read_b128 v[80:83], v137 offset:0
	v_mfma_f32_16x16x32_bf16 v[8:11], v[64:67], v[104:107], v[8:11]
	v_mfma_f32_16x16x32_bf16 v[12:15], v[64:67], v[108:111], v[12:15]
	ds_read_b128 v[112:115], v141 offset:0
	s_waitcnt lgkmcnt(4)
	v_mfma_f32_16x16x32_bf16 v[16:19], v[68:71], v[96:99], v[16:19]
	v_mfma_f32_16x16x32_bf16 v[20:23], v[68:71], v[100:103], v[20:23]
	ds_read_b128 v[116:119], v141 offset:2048
	v_mfma_f32_16x16x32_bf16 v[24:27], v[68:71], v[104:107], v[24:27]
	v_mfma_f32_16x16x32_bf16 v[28:31], v[68:71], v[108:111], v[28:31]
	ds_read_b128 v[120:123], v141 offset:4096
	s_waitcnt lgkmcnt(5)
	v_mfma_f32_16x16x32_bf16 v[32:35], v[72:75], v[96:99], v[32:35]
	v_mfma_f32_16x16x32_bf16 v[36:39], v[72:75], v[100:103], v[36:39]
	ds_read_b128 v[124:127], v141 offset:6144
	v_mfma_f32_16x16x32_bf16 v[40:43], v[72:75], v[104:107], v[40:43]
	v_mfma_f32_16x16x32_bf16 v[44:47], v[72:75], v[108:111], v[44:47]
	ds_read_b128 v[84:87], v137 offset:2048
	s_waitcnt lgkmcnt(6)
	v_mfma_f32_16x16x32_bf16 v[48:51], v[76:79], v[96:99], v[48:51]
	v_mfma_f32_16x16x32_bf16 v[52:55], v[76:79], v[100:103], v[52:55]
	ds_read_b128 v[88:91], v137 offset:4096
	v_mfma_f32_16x16x32_bf16 v[56:59], v[76:79], v[104:107], v[56:59]
	v_mfma_f32_16x16x32_bf16 v[60:63], v[76:79], v[108:111], v[60:63]
	ds_read_b128 v[92:95], v137 offset:6144
	s_waitcnt lgkmcnt(3)
	v_mfma_f32_16x16x32_bf16 v[0:3], v[80:83], v[112:115], v[0:3]
	v_mfma_f32_16x16x32_bf16 v[4:7], v[80:83], v[116:119], v[4:7]
	v_mfma_f32_16x16x32_bf16 v[8:11], v[80:83], v[120:123], v[8:11]
	v_mfma_f32_16x16x32_bf16 v[12:15], v[80:83], v[124:127], v[12:15]
	s_waitcnt lgkmcnt(2)
	v_mfma_f32_16x16x32_bf16 v[16:19], v[84:87], v[112:115], v[16:19]
	v_mfma_f32_16x16x32_bf16 v[20:23], v[84:87], v[116:119], v[20:23]
	v_mfma_f32_16x16x32_bf16 v[24:27], v[84:87], v[120:123], v[24:27]
	v_mfma_f32_16x16x32_bf16 v[28:31], v[84:87], v[124:127], v[28:31]
	s_waitcnt lgkmcnt(1)
	v_mfma_f32_16x16x32_bf16 v[32:35], v[88:91], v[112:115], v[32:35]
	v_mfma_f32_16x16x32_bf16 v[36:39], v[88:91], v[116:119], v[36:39]
	v_mfma_f32_16x16x32_bf16 v[40:43], v[88:91], v[120:123], v[40:43]
	v_mfma_f32_16x16x32_bf16 v[44:47], v[88:91], v[124:127], v[44:47]
	s_waitcnt lgkmcnt(0)
	v_mfma_f32_16x16x32_bf16 v[48:51], v[92:95], v[112:115], v[48:51]
	v_mfma_f32_16x16x32_bf16 v[52:55], v[92:95], v[116:119], v[52:55]
	v_mfma_f32_16x16x32_bf16 v[56:59], v[92:95], v[120:123], v[56:59]
	v_mfma_f32_16x16x32_bf16 v[60:63], v[92:95], v[124:127], v[60:63]
	s_waitcnt vmcnt(0)
	s_barrier
	s_add_i32 s99, s99, 1
	s_cmp_eq_u32 s99, 16
	s_movk_i32 s0, 0x80
	s_cselect_b32 s0, 0xfffff880, s0
	s_cselect_b32 s99, 0, s99
	s_ashr_i32 s1, s0, 31
	s_add_u32 s26, s26, s0
	s_addc_u32 s27, s27, s1
	s_add_u32 s28, s28, s0
	s_addc_u32 s29, s29, s1
	s_mov_b32 m0, s5
	s_nop 0
	global_load_lds_dwordx4 v132, s[26:27] offset:0
	global_load_lds_dwordx4 v133, s[26:27] offset:1024
	global_load_lds_dwordx4 v134, s[26:27] offset:2048
	global_load_lds_dwordx4 v135, s[26:27] offset:3072
	s_mov_b32 m0, s6
	s_nop 0
	global_load_lds_dwordx4 v132, s[28:29] offset:0
	global_load_lds_dwordx4 v133, s[28:29] offset:1024
	global_load_lds_dwordx4 v134, s[28:29] offset:2048
	global_load_lds_dwordx4 v135, s[28:29] offset:3072
	ds_read_b128 v[64:67], v138 offset:0
	ds_read_b128 v[96:99], v142 offset:0
	ds_read_b128 v[100:103], v142 offset:2048
	ds_read_b128 v[104:107], v142 offset:4096
	ds_read_b128 v[108:111], v142 offset:6144
	ds_read_b128 v[68:71], v138 offset:2048
	ds_read_b128 v[72:75], v138 offset:4096
	ds_read_b128 v[76:79], v138 offset:6144
	s_waitcnt lgkmcnt(3)
	v_mfma_f32_16x16x32_bf16 v[0:3], v[64:67], v[96:99], v[0:3]
	v_mfma_f32_16x16x32_bf16 v[4:7], v[64:67], v[100:103], v[4:7]
	ds_read_b128 v[80:83], v139 offset:0
	v_mfma_f32_16x16x32_bf16 v[8:11], v[64:67], v[104:107], v[8:11]
	v_mfma_f32_16x16x32_bf16 v[12:15], v[64:67], v[108:111], v[12:15]
	ds_read_b128 v[112:115], v143 offset:0
	s_waitcnt lgkmcnt(4)
	v_mfma_f32_16x16x32_bf16 v[16:19], v[68:71], v[96:99], v[16:19]
	v_mfma_f32_16x16x32_bf16 v[20:23], v[68:71], v[100:103], v[20:23]
	ds_read_b128 v[116:119], v143 offset:2048
	v_mfma_f32_16x16x32_bf16 v[24:27], v[68:71], v[104:107], v[24:27]
	v_mfma_f32_16x16x32_bf16 v[28:31], v[68:71], v[108:111], v[28:31]
	ds_read_b128 v[120:123], v143 offset:4096
	s_waitcnt lgkmcnt(5)
	v_mfma_f32_16x16x32_bf16 v[32:35], v[72:75], v[96:99], v[32:35]
	v_mfma_f32_16x16x32_bf16 v[36:39], v[72:75], v[100:103], v[36:39]
	ds_read_b128 v[124:127], v143 offset:6144
	v_mfma_f32_16x16x32_bf16 v[40:43], v[72:75], v[104:107], v[40:43]
	v_mfma_f32_16x16x32_bf16 v[44:47], v[72:75], v[108:111], v[44:47]
	ds_read_b128 v[84:87], v139 offset:2048
	s_waitcnt lgkmcnt(6)
	v_mfma_f32_16x16x32_bf16 v[48:51], v[76:79], v[96:99], v[48:51]
	v_mfma_f32_16x16x32_bf16 v[52:55], v[76:79], v[100:103], v[52:55]
	ds_read_b128 v[88:91], v139 offset:4096
	v_mfma_f32_16x16x32_bf16 v[56:59], v[76:79], v[104:107], v[56:59]
	v_mfma_f32_16x16x32_bf16 v[60:63], v[76:79], v[108:111], v[60:63]
	ds_read_b128 v[92:95], v139 offset:6144
	s_waitcnt lgkmcnt(3)
	v_mfma_f32_16x16x32_bf16 v[0:3], v[80:83], v[112:115], v[0:3]
	v_mfma_f32_16x16x32_bf16 v[4:7], v[80:83], v[116:119], v[4:7]
	v_mfma_f32_16x16x32_bf16 v[8:11], v[80:83], v[120:123], v[8:11]
	v_mfma_f32_16x16x32_bf16 v[12:15], v[80:83], v[124:127], v[12:15]
	s_waitcnt lgkmcnt(2)
	v_mfma_f32_16x16x32_bf16 v[16:19], v[84:87], v[112:115], v[16:19]
	v_mfma_f32_16x16x32_bf16 v[20:23], v[84:87], v[116:119], v[20:23]
	v_mfma_f32_16x16x32_bf16 v[24:27], v[84:87], v[120:123], v[24:27]
	v_mfma_f32_16x16x32_bf16 v[28:31], v[84:87], v[124:127], v[28:31]
	s_waitcnt lgkmcnt(1)
	v_mfma_f32_16x16x32_bf16 v[32:35], v[88:91], v[112:115], v[32:35]
	v_mfma_f32_16x16x32_bf16 v[36:39], v[88:91], v[116:119], v[36:39]
	v_mfma_f32_16x16x32_bf16 v[40:43], v[88:91], v[120:123], v[40:43]
	v_mfma_f32_16x16x32_bf16 v[44:47], v[88:91], v[124:127], v[44:47]
	s_waitcnt lgkmcnt(0)
	v_mfma_f32_16x16x32_bf16 v[48:51], v[92:95], v[112:115], v[48:51]
	v_mfma_f32_16x16x32_bf16 v[52:55], v[92:95], v[116:119], v[52:55]
	v_mfma_f32_16x16x32_bf16 v[56:59], v[92:95], v[120:123], v[56:59]
	v_mfma_f32_16x16x32_bf16 v[60:63], v[92:95], v[124:127], v[60:63]
	s_waitcnt vmcnt(0)
	s_barrier
	s_add_i32 s99, s99, 1
	s_cmp_eq_u32 s99, 16
	s_movk_i32 s0, 0x80
	s_cselect_b32 s0, 0xfffff880, s0
	s_cselect_b32 s99, 0, s99
	s_ashr_i32 s1, s0, 31
	s_add_u32 s26, s26, s0
	s_addc_u32 s27, s27, s1
	s_add_u32 s28, s28, s0
	s_addc_u32 s29, s29, s1
	s_mov_b32 m0, s7
	s_nop 0
	global_load_lds_dwordx4 v132, s[26:27] offset:0
	global_load_lds_dwordx4 v133, s[26:27] offset:1024
	global_load_lds_dwordx4 v134, s[26:27] offset:2048
	global_load_lds_dwordx4 v135, s[26:27] offset:3072
	s_mov_b32 m0, s8
	s_nop 0
	global_load_lds_dwordx4 v132, s[28:29] offset:0
	global_load_lds_dwordx4 v133, s[28:29] offset:1024
	global_load_lds_dwordx4 v134, s[28:29] offset:2048
	global_load_lds_dwordx4 v135, s[28:29] offset:3072
	ds_read_b128 v[64:67], v136 offset:0
	ds_read_b128 v[96:99], v140 offset:0
	ds_read_b128 v[100:103], v140 offset:2048
	ds_read_b128 v[104:107], v140 offset:4096
	ds_read_b128 v[108:111], v140 offset:6144
	ds_read_b128 v[68:71], v136 offset:2048
	ds_read_b128 v[72:75], v136 offset:4096
	ds_read_b128 v[76:79], v136 offset:6144
	s_waitcnt lgkmcnt(3)
	v_mfma_f32_16x16x32_bf16 v[0:3], v[64:67], v[96:99], v[0:3]
	v_mfma_f32_16x16x32_bf16 v[4:7], v[64:67], v[100:103], v[4:7]
	ds_read_b128 v[80:83], v137 offset:0
	v_mfma_f32_16x16x32_bf16 v[8:11], v[64:67], v[104:107], v[8:11]
	v_mfma_f32_16x16x32_bf16 v[12:15], v[64:67], v[108:111], v[12:15]
	ds_read_b128 v[112:115], v141 offset:0
	s_waitcnt lgkmcnt(4)
	v_mfma_f32_16x16x32_bf16 v[16:19], v[68:71], v[96:99], v[16:19]
	v_mfma_f32_16x16x32_bf16 v[20:23], v[68:71], v[100:103], v[20:23]
	ds_read_b128 v[116:119], v141 offset:2048
	v_mfma_f32_16x16x32_bf16 v[24:27], v[68:71], v[104:107], v[24:27]
	v_mfma_f32_16x16x32_bf16 v[28:31], v[68:71], v[108:111], v[28:31]
	ds_read_b128 v[120:123], v141 offset:4096
	s_waitcnt lgkmcnt(5)
	v_mfma_f32_16x16x32_bf16 v[32:35], v[72:75], v[96:99], v[32:35]
	v_mfma_f32_16x16x32_bf16 v[36:39], v[72:75], v[100:103], v[36:39]
	ds_read_b128 v[124:127], v141 offset:6144
	v_mfma_f32_16x16x32_bf16 v[40:43], v[72:75], v[104:107], v[40:43]
	v_mfma_f32_16x16x32_bf16 v[44:47], v[72:75], v[108:111], v[44:47]
	ds_read_b128 v[84:87], v137 offset:2048
	s_waitcnt lgkmcnt(6)
	v_mfma_f32_16x16x32_bf16 v[48:51], v[76:79], v[96:99], v[48:51]
	v_mfma_f32_16x16x32_bf16 v[52:55], v[76:79], v[100:103], v[52:55]
	ds_read_b128 v[88:91], v137 offset:4096
	v_mfma_f32_16x16x32_bf16 v[56:59], v[76:79], v[104:107], v[56:59]
	v_mfma_f32_16x16x32_bf16 v[60:63], v[76:79], v[108:111], v[60:63]
	ds_read_b128 v[92:95], v137 offset:6144
	s_waitcnt lgkmcnt(3)
	v_mfma_f32_16x16x32_bf16 v[0:3], v[80:83], v[112:115], v[0:3]
	v_mfma_f32_16x16x32_bf16 v[4:7], v[80:83], v[116:119], v[4:7]
	v_mfma_f32_16x16x32_bf16 v[8:11], v[80:83], v[120:123], v[8:11]
	v_mfma_f32_16x16x32_bf16 v[12:15], v[80:83], v[124:127], v[12:15]
	s_waitcnt lgkmcnt(2)
	v_mfma_f32_16x16x32_bf16 v[16:19], v[84:87], v[112:115], v[16:19]
	v_mfma_f32_16x16x32_bf16 v[20:23], v[84:87], v[116:119], v[20:23]
	v_mfma_f32_16x16x32_bf16 v[24:27], v[84:87], v[120:123], v[24:27]
	v_mfma_f32_16x16x32_bf16 v[28:31], v[84:87], v[124:127], v[28:31]
	s_waitcnt lgkmcnt(1)
	v_mfma_f32_16x16x32_bf16 v[32:35], v[88:91], v[112:115], v[32:35]
	v_mfma_f32_16x16x32_bf16 v[36:39], v[88:91], v[116:119], v[36:39]
	v_mfma_f32_16x16x32_bf16 v[40:43], v[88:91], v[120:123], v[40:43]
	v_mfma_f32_16x16x32_bf16 v[44:47], v[88:91], v[124:127], v[44:47]
	s_waitcnt lgkmcnt(0)
	v_mfma_f32_16x16x32_bf16 v[48:51], v[92:95], v[112:115], v[48:51]
	v_mfma_f32_16x16x32_bf16 v[52:55], v[92:95], v[116:119], v[52:55]
	v_mfma_f32_16x16x32_bf16 v[56:59], v[92:95], v[120:123], v[56:59]
	v_mfma_f32_16x16x32_bf16 v[60:63], v[92:95], v[124:127], v[60:63]
	s_waitcnt vmcnt(0)
	s_barrier
	s_add_i32 s99, s99, 1
	s_cmp_eq_u32 s99, 16
	s_movk_i32 s0, 0x80
	s_cselect_b32 s0, 0xfffff880, s0
	s_cselect_b32 s99, 0, s99
	s_ashr_i32 s1, s0, 31
	s_add_u32 s26, s26, s0
	s_addc_u32 s27, s27, s1
	s_add_u32 s28, s28, s0
	s_addc_u32 s29, s29, s1
	s_mov_b32 m0, s5
	s_nop 0
	global_load_lds_dwordx4 v132, s[26:27] offset:0
	global_load_lds_dwordx4 v133, s[26:27] offset:1024
	global_load_lds_dwordx4 v134, s[26:27] offset:2048
	global_load_lds_dwordx4 v135, s[26:27] offset:3072
	s_mov_b32 m0, s6
	s_nop 0
	global_load_lds_dwordx4 v132, s[28:29] offset:0
	global_load_lds_dwordx4 v133, s[28:29] offset:1024
	global_load_lds_dwordx4 v134, s[28:29] offset:2048
	global_load_lds_dwordx4 v135, s[28:29] offset:3072
	ds_read_b128 v[64:67], v138 offset:0
	ds_read_b128 v[96:99], v142 offset:0
	ds_read_b128 v[100:103], v142 offset:2048
	ds_read_b128 v[104:107], v142 offset:4096
	ds_read_b128 v[108:111], v142 offset:6144
	ds_read_b128 v[68:71], v138 offset:2048
	ds_read_b128 v[72:75], v138 offset:4096
	ds_read_b128 v[76:79], v138 offset:6144
	s_waitcnt lgkmcnt(3)
	v_mfma_f32_16x16x32_bf16 v[0:3], v[64:67], v[96:99], v[0:3]
	v_mfma_f32_16x16x32_bf16 v[4:7], v[64:67], v[100:103], v[4:7]
	ds_read_b128 v[80:83], v139 offset:0
	v_mfma_f32_16x16x32_bf16 v[8:11], v[64:67], v[104:107], v[8:11]
	v_mfma_f32_16x16x32_bf16 v[12:15], v[64:67], v[108:111], v[12:15]
	ds_read_b128 v[112:115], v143 offset:0
	s_waitcnt lgkmcnt(4)
	v_mfma_f32_16x16x32_bf16 v[16:19], v[68:71], v[96:99], v[16:19]
	v_mfma_f32_16x16x32_bf16 v[20:23], v[68:71], v[100:103], v[20:23]
	ds_read_b128 v[116:119], v143 offset:2048
	v_mfma_f32_16x16x32_bf16 v[24:27], v[68:71], v[104:107], v[24:27]
	v_mfma_f32_16x16x32_bf16 v[28:31], v[68:71], v[108:111], v[28:31]
	ds_read_b128 v[120:123], v143 offset:4096
	s_waitcnt lgkmcnt(5)
	v_mfma_f32_16x16x32_bf16 v[32:35], v[72:75], v[96:99], v[32:35]
	v_mfma_f32_16x16x32_bf16 v[36:39], v[72:75], v[100:103], v[36:39]
	ds_read_b128 v[124:127], v143 offset:6144
	v_mfma_f32_16x16x32_bf16 v[40:43], v[72:75], v[104:107], v[40:43]
	v_mfma_f32_16x16x32_bf16 v[44:47], v[72:75], v[108:111], v[44:47]
	ds_read_b128 v[84:87], v139 offset:2048
	s_waitcnt lgkmcnt(6)
	v_mfma_f32_16x16x32_bf16 v[48:51], v[76:79], v[96:99], v[48:51]
	v_mfma_f32_16x16x32_bf16 v[52:55], v[76:79], v[100:103], v[52:55]
	ds_read_b128 v[88:91], v139 offset:4096
	v_mfma_f32_16x16x32_bf16 v[56:59], v[76:79], v[104:107], v[56:59]
	v_mfma_f32_16x16x32_bf16 v[60:63], v[76:79], v[108:111], v[60:63]
	ds_read_b128 v[92:95], v139 offset:6144
	s_waitcnt lgkmcnt(3)
	v_mfma_f32_16x16x32_bf16 v[0:3], v[80:83], v[112:115], v[0:3]
	v_mfma_f32_16x16x32_bf16 v[4:7], v[80:83], v[116:119], v[4:7]
	v_mfma_f32_16x16x32_bf16 v[8:11], v[80:83], v[120:123], v[8:11]
	v_mfma_f32_16x16x32_bf16 v[12:15], v[80:83], v[124:127], v[12:15]
	s_waitcnt lgkmcnt(2)
	v_mfma_f32_16x16x32_bf16 v[16:19], v[84:87], v[112:115], v[16:19]
	v_mfma_f32_16x16x32_bf16 v[20:23], v[84:87], v[116:119], v[20:23]
	v_mfma_f32_16x16x32_bf16 v[24:27], v[84:87], v[120:123], v[24:27]
	v_mfma_f32_16x16x32_bf16 v[28:31], v[84:87], v[124:127], v[28:31]
	s_waitcnt lgkmcnt(1)
	v_mfma_f32_16x16x32_bf16 v[32:35], v[88:91], v[112:115], v[32:35]
	v_mfma_f32_16x16x32_bf16 v[36:39], v[88:91], v[116:119], v[36:39]
	v_mfma_f32_16x16x32_bf16 v[40:43], v[88:91], v[120:123], v[40:43]
	v_mfma_f32_16x16x32_bf16 v[44:47], v[88:91], v[124:127], v[44:47]
	s_waitcnt lgkmcnt(0)
	v_mfma_f32_16x16x32_bf16 v[48:51], v[92:95], v[112:115], v[48:51]
	v_mfma_f32_16x16x32_bf16 v[52:55], v[92:95], v[116:119], v[52:55]
	v_mfma_f32_16x16x32_bf16 v[56:59], v[92:95], v[120:123], v[56:59]
	v_mfma_f32_16x16x32_bf16 v[60:63], v[92:95], v[124:127], v[60:63]
	s_waitcnt vmcnt(0)
	s_barrier
	s_add_i32 s99, s99, 1
	s_cmp_eq_u32 s99, 16
	s_movk_i32 s0, 0x80
	s_cselect_b32 s0, 0xfffff880, s0
	s_cselect_b32 s99, 0, s99
	s_ashr_i32 s1, s0, 31
	s_add_u32 s26, s26, s0
	s_addc_u32 s27, s27, s1
	s_add_u32 s28, s28, s0
	s_addc_u32 s29, s29, s1
	s_mov_b32 m0, s7
	s_nop 0
	global_load_lds_dwordx4 v132, s[26:27] offset:0
	global_load_lds_dwordx4 v133, s[26:27] offset:1024
	global_load_lds_dwordx4 v134, s[26:27] offset:2048
	global_load_lds_dwordx4 v135, s[26:27] offset:3072
	s_mov_b32 m0, s8
	s_nop 0
	global_load_lds_dwordx4 v132, s[28:29] offset:0
	global_load_lds_dwordx4 v133, s[28:29] offset:1024
	global_load_lds_dwordx4 v134, s[28:29] offset:2048
	global_load_lds_dwordx4 v135, s[28:29] offset:3072
	ds_read_b128 v[64:67], v136 offset:0
	ds_read_b128 v[96:99], v140 offset:0
	ds_read_b128 v[100:103], v140 offset:2048
	ds_read_b128 v[104:107], v140 offset:4096
	ds_read_b128 v[108:111], v140 offset:6144
	ds_read_b128 v[68:71], v136 offset:2048
	ds_read_b128 v[72:75], v136 offset:4096
	ds_read_b128 v[76:79], v136 offset:6144
	s_waitcnt lgkmcnt(3)
	v_mfma_f32_16x16x32_bf16 v[0:3], v[64:67], v[96:99], v[0:3]
	v_mfma_f32_16x16x32_bf16 v[4:7], v[64:67], v[100:103], v[4:7]
	ds_read_b128 v[80:83], v137 offset:0
	v_mfma_f32_16x16x32_bf16 v[8:11], v[64:67], v[104:107], v[8:11]
	v_mfma_f32_16x16x32_bf16 v[12:15], v[64:67], v[108:111], v[12:15]
	ds_read_b128 v[112:115], v141 offset:0
	s_waitcnt lgkmcnt(4)
	v_mfma_f32_16x16x32_bf16 v[16:19], v[68:71], v[96:99], v[16:19]
	v_mfma_f32_16x16x32_bf16 v[20:23], v[68:71], v[100:103], v[20:23]
	ds_read_b128 v[116:119], v141 offset:2048
	v_mfma_f32_16x16x32_bf16 v[24:27], v[68:71], v[104:107], v[24:27]
	v_mfma_f32_16x16x32_bf16 v[28:31], v[68:71], v[108:111], v[28:31]
	ds_read_b128 v[120:123], v141 offset:4096
	s_waitcnt lgkmcnt(5)
	v_mfma_f32_16x16x32_bf16 v[32:35], v[72:75], v[96:99], v[32:35]
	v_mfma_f32_16x16x32_bf16 v[36:39], v[72:75], v[100:103], v[36:39]
	ds_read_b128 v[124:127], v141 offset:6144
	v_mfma_f32_16x16x32_bf16 v[40:43], v[72:75], v[104:107], v[40:43]
	v_mfma_f32_16x16x32_bf16 v[44:47], v[72:75], v[108:111], v[44:47]
	ds_read_b128 v[84:87], v137 offset:2048
	s_waitcnt lgkmcnt(6)
	v_mfma_f32_16x16x32_bf16 v[48:51], v[76:79], v[96:99], v[48:51]
	v_mfma_f32_16x16x32_bf16 v[52:55], v[76:79], v[100:103], v[52:55]
	ds_read_b128 v[88:91], v137 offset:4096
	v_mfma_f32_16x16x32_bf16 v[56:59], v[76:79], v[104:107], v[56:59]
	v_mfma_f32_16x16x32_bf16 v[60:63], v[76:79], v[108:111], v[60:63]
	ds_read_b128 v[92:95], v137 offset:6144
	s_waitcnt lgkmcnt(3)
	v_mfma_f32_16x16x32_bf16 v[0:3], v[80:83], v[112:115], v[0:3]
	v_mfma_f32_16x16x32_bf16 v[4:7], v[80:83], v[116:119], v[4:7]
	v_mfma_f32_16x16x32_bf16 v[8:11], v[80:83], v[120:123], v[8:11]
	v_mfma_f32_16x16x32_bf16 v[12:15], v[80:83], v[124:127], v[12:15]
	s_waitcnt lgkmcnt(2)
	v_mfma_f32_16x16x32_bf16 v[16:19], v[84:87], v[112:115], v[16:19]
	v_mfma_f32_16x16x32_bf16 v[20:23], v[84:87], v[116:119], v[20:23]
	v_mfma_f32_16x16x32_bf16 v[24:27], v[84:87], v[120:123], v[24:27]
	v_mfma_f32_16x16x32_bf16 v[28:31], v[84:87], v[124:127], v[28:31]
	s_waitcnt lgkmcnt(1)
	v_mfma_f32_16x16x32_bf16 v[32:35], v[88:91], v[112:115], v[32:35]
	v_mfma_f32_16x16x32_bf16 v[36:39], v[88:91], v[116:119], v[36:39]
	v_mfma_f32_16x16x32_bf16 v[40:43], v[88:91], v[120:123], v[40:43]
	v_mfma_f32_16x16x32_bf16 v[44:47], v[88:91], v[124:127], v[44:47]
	s_waitcnt lgkmcnt(0)
	v_mfma_f32_16x16x32_bf16 v[48:51], v[92:95], v[112:115], v[48:51]
	v_mfma_f32_16x16x32_bf16 v[52:55], v[92:95], v[116:119], v[52:55]
	v_mfma_f32_16x16x32_bf16 v[56:59], v[92:95], v[120:123], v[56:59]
	v_mfma_f32_16x16x32_bf16 v[60:63], v[92:95], v[124:127], v[60:63]
	s_waitcnt vmcnt(0)
	s_barrier
	ds_read_b128 v[64:67], v138 offset:0
	ds_read_b128 v[96:99], v142 offset:0
	ds_read_b128 v[100:103], v142 offset:2048
	ds_read_b128 v[104:107], v142 offset:4096
	ds_read_b128 v[108:111], v142 offset:6144
	ds_read_b128 v[68:71], v138 offset:2048
	ds_read_b128 v[72:75], v138 offset:4096
	ds_read_b128 v[76:79], v138 offset:6144
	s_waitcnt lgkmcnt(3)
	v_mfma_f32_16x16x32_bf16 v[0:3], v[64:67], v[96:99], v[0:3]
	v_mfma_f32_16x16x32_bf16 v[4:7], v[64:67], v[100:103], v[4:7]
	ds_read_b128 v[80:83], v139 offset:0
	v_mfma_f32_16x16x32_bf16 v[8:11], v[64:67], v[104:107], v[8:11]
	v_mfma_f32_16x16x32_bf16 v[12:15], v[64:67], v[108:111], v[12:15]
	ds_read_b128 v[112:115], v143 offset:0
	s_waitcnt lgkmcnt(4)
	v_mfma_f32_16x16x32_bf16 v[16:19], v[68:71], v[96:99], v[16:19]
	v_mfma_f32_16x16x32_bf16 v[20:23], v[68:71], v[100:103], v[20:23]
	ds_read_b128 v[116:119], v143 offset:2048
	v_mfma_f32_16x16x32_bf16 v[24:27], v[68:71], v[104:107], v[24:27]
	v_mfma_f32_16x16x32_bf16 v[28:31], v[68:71], v[108:111], v[28:31]
	ds_read_b128 v[120:123], v143 offset:4096
	s_waitcnt lgkmcnt(5)
	v_mfma_f32_16x16x32_bf16 v[32:35], v[72:75], v[96:99], v[32:35]
	v_mfma_f32_16x16x32_bf16 v[36:39], v[72:75], v[100:103], v[36:39]
	ds_read_b128 v[124:127], v143 offset:6144
	v_mfma_f32_16x16x32_bf16 v[40:43], v[72:75], v[104:107], v[40:43]
	v_mfma_f32_16x16x32_bf16 v[44:47], v[72:75], v[108:111], v[44:47]
	ds_read_b128 v[84:87], v139 offset:2048
	s_waitcnt lgkmcnt(6)
	v_mfma_f32_16x16x32_bf16 v[48:51], v[76:79], v[96:99], v[48:51]
	v_mfma_f32_16x16x32_bf16 v[52:55], v[76:79], v[100:103], v[52:55]
	ds_read_b128 v[88:91], v139 offset:4096
	v_mfma_f32_16x16x32_bf16 v[56:59], v[76:79], v[104:107], v[56:59]
	v_mfma_f32_16x16x32_bf16 v[60:63], v[76:79], v[108:111], v[60:63]
	ds_read_b128 v[92:95], v139 offset:6144
	s_waitcnt lgkmcnt(3)
	v_mfma_f32_16x16x32_bf16 v[0:3], v[80:83], v[112:115], v[0:3]
	v_mfma_f32_16x16x32_bf16 v[4:7], v[80:83], v[116:119], v[4:7]
	v_mfma_f32_16x16x32_bf16 v[8:11], v[80:83], v[120:123], v[8:11]
	v_mfma_f32_16x16x32_bf16 v[12:15], v[80:83], v[124:127], v[12:15]
	s_waitcnt lgkmcnt(2)
	v_mfma_f32_16x16x32_bf16 v[16:19], v[84:87], v[112:115], v[16:19]
	v_mfma_f32_16x16x32_bf16 v[20:23], v[84:87], v[116:119], v[20:23]
	v_mfma_f32_16x16x32_bf16 v[24:27], v[84:87], v[120:123], v[24:27]
	v_mfma_f32_16x16x32_bf16 v[28:31], v[84:87], v[124:127], v[28:31]
	s_waitcnt lgkmcnt(1)
	v_mfma_f32_16x16x32_bf16 v[32:35], v[88:91], v[112:115], v[32:35]
	v_mfma_f32_16x16x32_bf16 v[36:39], v[88:91], v[116:119], v[36:39]
	v_mfma_f32_16x16x32_bf16 v[40:43], v[88:91], v[120:123], v[40:43]
	v_mfma_f32_16x16x32_bf16 v[44:47], v[88:91], v[124:127], v[44:47]
	s_waitcnt lgkmcnt(0)
	v_mfma_f32_16x16x32_bf16 v[48:51], v[92:95], v[112:115], v[48:51]
	v_mfma_f32_16x16x32_bf16 v[52:55], v[92:95], v[116:119], v[52:55]
	v_mfma_f32_16x16x32_bf16 v[56:59], v[92:95], v[120:123], v[56:59]
	v_mfma_f32_16x16x32_bf16 v[60:63], v[92:95], v[124:127], v[60:63]
	s_cmp_lt_i32 s100, 0
	s_cbranch_scc0 .Lgin_perm
	v_readlane_b32 s38, v255, 35
	s_nop 0
	s_add_i32 s38, s25, s38
	s_branch .Lgin_have
.Lgin_perm:
	s_add_i32 s100, s100, 1
	s_cmp_lt_u32 s100, 9
	s_cbranch_scc0 .Lgin_r9
	s_and_b32 s0, s101, 7
	s_add_i32 s0, s0, s100
	s_cmp_ge_u32 s0, 9
	s_cbranch_scc0 .Lgin_rk
	s_sub_u32 s0, s0, 9
